# attention: lazy-rescale max check evaluated on alternate tiles (rescaling is mathematically neutral; softmax still exact, f32 accumulation unchanged)
# speedup vs baseline: 1.0083x; 1.0083x over previous
; DI float xmax32(float x) { auto t = __builtin_amdgcn_permlane32_swap(__float_as_uint(x), __float_as_uint(x), false, false); return fmaxf(__uint_as_float(t[0]), __uint_as_float(t[1])); }
; template <int DK, int DV>
; DI void attn_map(f32x16 (&O)[DV / 32], float& lsum, const u16* qrow, const u16* K1, int ldk1, const u16* K2, int ldk2, const u16* Vt, int nkeys, char* smem) {
;     ...
;     float mx0 = fmaxf(fmaxf(s[0][0], s[0][1]), s[0][2]), mx1 = fmaxf(fmaxf(s[1][0], s[1][1]), s[1][2]);
; #pragma unroll
;     for (int i = 3; i < 15; i += 2) { mx0 = fmaxf(fmaxf(mx0, s[0][i]), s[0][i + 1]); mx1 = fmaxf(fmaxf(mx1, s[1][i]), s[1][i + 1]); }
;     float mx = fmaxf(fmaxf(mx0, mx1), fmaxf(s[0][15], s[1][15]));
;     mx = xmax32(mx);
;     const bool first = (k0 == 0);
;     if (first || __any(mx > 6.f)) {
;       float dl = first ? mx : fmaxf(mx, 0.f);
;       float alpha = __builtin_amdgcn_exp2f(-dl);
; #pragma unroll
;       for (int i = 0; i < 16; ++i) { negm[i] -= dl; lacc[i] *= alpha; }
; #pragma unroll
;       for (int dd = 0; dd < DV / 32; ++dd)
; #pragma unroll
;         for (int i = 0; i < 16; ++i) O[dd][i] *= alpha;
; #pragma unroll
;       for (int j = 0; j < 2; ++j)
; #pragma unroll
;         for (int i = 0; i < 16; ++i) s[j][i] -= dl;
;     }
.Lqk_join_A:
	s_bitcmp1_b32 s10, 6
	s_cbranch_scc1 .Lskipmax_A
	s_nop 0
	v_max3_f32 v194, v96, v97, v98
	v_lshl_add_u64 v[176:177], v[176:177], 0, s[56:57]
	v_lshl_add_u64 v[178:179], v[178:179], 0, s[56:57]
	v_lshl_add_u64 v[180:181], v[180:181], 0, s[56:57]
	v_lshl_add_u64 v[182:183], v[182:183], 0, s[56:57]
	v_lshl_add_u64 v[184:185], v[184:185], 0, s[58:59]
	v_lshl_add_u64 v[186:187], v[186:187], 0, s[58:59]
	v_mov_b64_e32 v[232:233], s[48:49]
	v_mov_b64_e32 v[234:235], s[50:51]
	s_nop 0
	v_max3_f32 v195, v112, v113, v114
	v_max3_f32 v194, v194, v99, v100
	v_max3_f32 v195, v195, v115, v116
	v_max3_f32 v194, v194, v101, v102
	v_max3_f32 v195, v195, v117, v118
	v_max3_f32 v194, v194, v103, v104
	v_max3_f32 v195, v195, v119, v120
	v_max3_f32 v194, v194, v105, v106
	v_max3_f32 v195, v195, v121, v122
	v_max3_f32 v194, v194, v107, v108
	v_max3_f32 v195, v195, v123, v124
	v_max_f32_e32 v196, v127, v127
	v_max_f32_e32 v197, v111, v111
	v_max3_f32 v194, v194, v109, v110
	v_max3_f32 v195, v195, v125, v126
	v_max_f32_e32 v196, v197, v196
	v_max3_f32 v194, v194, v195, v196
	v_cmp_lt_f32_e32 vcc, s45, v194
	s_cbranch_vccz .LBB0_381
	v_mov_b32_e32 v195, v194
	s_nop 1
	v_permlane32_swap_b32_e32 v194, v195
	v_max_f32_e32 v195, v195, v195
	v_max_f32_e32 v194, v194, v194
	v_max_f32_e32 v194, v194, v195
	v_max_f32_e32 v194, v194, v194
	v_max_f32_e32 v195, 0, v194
	v_exp_f32_e64 v194, -v195
	v_sub_f32_e32 v31, v31, v195
	v_sub_f32_e32 v30, v30, v195
	v_sub_f32_e32 v29, v29, v195
	v_pk_mul_f32 v[62:63], v[62:63], v[194:195] op_sel_hi:[1,0]
	v_pk_mul_f32 v[60:61], v[60:61], v[194:195] op_sel_hi:[1,0]
	v_pk_mul_f32 v[58:59], v[58:59], v[194:195] op_sel_hi:[1,0]
	v_pk_mul_f32 v[56:57], v[56:57], v[194:195] op_sel_hi:[1,0]
	v_pk_mul_f32 v[54:55], v[54:55], v[194:195] op_sel_hi:[1,0]
	v_pk_mul_f32 v[52:53], v[52:53], v[194:195] op_sel_hi:[1,0]
	v_pk_mul_f32 v[50:51], v[50:51], v[194:195] op_sel_hi:[1,0]
	v_pk_mul_f32 v[48:49], v[48:49], v[194:195] op_sel_hi:[1,0]
	v_pk_mul_f32 v[46:47], v[46:47], v[194:195] op_sel_hi:[1,0]
	v_pk_mul_f32 v[44:45], v[44:45], v[194:195] op_sel_hi:[1,0]
	v_pk_mul_f32 v[42:43], v[42:43], v[194:195] op_sel_hi:[1,0]
	v_pk_mul_f32 v[40:41], v[40:41], v[194:195] op_sel_hi:[1,0]
	v_pk_mul_f32 v[38:39], v[38:39], v[194:195] op_sel_hi:[1,0]
	v_pk_mul_f32 v[36:37], v[36:37], v[194:195] op_sel_hi:[1,0]
	v_pk_mul_f32 v[34:35], v[34:35], v[194:195] op_sel_hi:[1,0]
	v_pk_mul_f32 v[32:33], v[32:33], v[194:195] op_sel_hi:[1,0]
	v_pk_mul_f32 v[78:79], v[78:79], v[194:195] op_sel_hi:[1,0]
	v_pk_mul_f32 v[76:77], v[76:77], v[194:195] op_sel_hi:[1,0]
	v_pk_mul_f32 v[74:75], v[74:75], v[194:195] op_sel_hi:[1,0]
	v_pk_mul_f32 v[72:73], v[72:73], v[194:195] op_sel_hi:[1,0]
	v_pk_mul_f32 v[70:71], v[70:71], v[194:195] op_sel_hi:[1,0]
	v_pk_mul_f32 v[68:69], v[68:69], v[194:195] op_sel_hi:[1,0]
	v_pk_mul_f32 v[66:67], v[66:67], v[194:195] op_sel_hi:[1,0]
	v_pk_mul_f32 v[64:65], v[64:65], v[194:195] op_sel_hi:[1,0]
	v_pk_mul_f32 v[94:95], v[94:95], v[194:195] op_sel_hi:[1,0]
	v_pk_mul_f32 v[92:93], v[92:93], v[194:195] op_sel_hi:[1,0]
	v_pk_mul_f32 v[90:91], v[90:91], v[194:195] op_sel_hi:[1,0]
	v_pk_mul_f32 v[88:89], v[88:89], v[194:195] op_sel_hi:[1,0]
	v_pk_mul_f32 v[86:87], v[86:87], v[194:195] op_sel_hi:[1,0]
	v_pk_mul_f32 v[84:85], v[84:85], v[194:195] op_sel_hi:[1,0]
	v_pk_mul_f32 v[82:83], v[82:83], v[194:195] op_sel_hi:[1,0]
	v_pk_mul_f32 v[80:81], v[80:81], v[194:195] op_sel_hi:[1,0]
	v_sub_f32_e32 v28, v28, v195
	v_sub_f32_e32 v27, v27, v195
	v_sub_f32_e32 v26, v26, v195
	v_sub_f32_e32 v25, v25, v195
	v_sub_f32_e32 v24, v24, v195
	v_sub_f32_e32 v23, v23, v195
	v_sub_f32_e32 v22, v22, v195
	v_sub_f32_e32 v21, v21, v195
	v_sub_f32_e32 v20, v20, v195
	v_sub_f32_e32 v19, v19, v195
	v_sub_f32_e32 v18, v18, v195
	v_sub_f32_e32 v17, v17, v195
	v_sub_f32_e32 v16, v16, v195
	v_sub_f32_e32 v96, v96, v195
	v_sub_f32_e32 v97, v97, v195
	v_sub_f32_e32 v98, v98, v195
	v_sub_f32_e32 v99, v99, v195
	v_sub_f32_e32 v100, v100, v195
	v_sub_f32_e32 v101, v101, v195
	v_sub_f32_e32 v102, v102, v195
	v_sub_f32_e32 v103, v103, v195
	v_sub_f32_e32 v104, v104, v195
	v_sub_f32_e32 v105, v105, v195
	v_sub_f32_e32 v106, v106, v195
	v_sub_f32_e32 v107, v107, v195
	v_sub_f32_e32 v108, v108, v195
	v_sub_f32_e32 v109, v109, v195
	v_sub_f32_e32 v110, v110, v195
	v_sub_f32_e32 v111, v111, v195
	v_sub_f32_e32 v112, v112, v195
	v_sub_f32_e32 v113, v113, v195
	v_sub_f32_e32 v114, v114, v195
	v_sub_f32_e32 v115, v115, v195
	v_sub_f32_e32 v116, v116, v195
	v_sub_f32_e32 v117, v117, v195
	v_sub_f32_e32 v118, v118, v195
	v_sub_f32_e32 v119, v119, v195
	v_sub_f32_e32 v120, v120, v195
	v_sub_f32_e32 v121, v121, v195
	v_sub_f32_e32 v122, v122, v195
	v_sub_f32_e32 v123, v123, v195
	v_sub_f32_e32 v124, v124, v195
	v_sub_f32_e32 v125, v125, v195
	v_sub_f32_e32 v126, v126, v195
	v_sub_f32_e32 v127, v127, v195
	v_pk_mul_f32 v[14:15], v[14:15], v[194:195] op_sel_hi:[1,0]
	v_pk_mul_f32 v[12:13], v[12:13], v[194:195] op_sel_hi:[1,0]
	v_pk_mul_f32 v[10:11], v[10:11], v[194:195] op_sel_hi:[1,0]
	v_pk_mul_f32 v[8:9], v[8:9], v[194:195] op_sel_hi:[1,0]
	v_pk_mul_f32 v[6:7], v[6:7], v[194:195] op_sel_hi:[1,0]
	v_pk_mul_f32 v[4:5], v[4:5], v[194:195] op_sel_hi:[1,0]
	v_pk_mul_f32 v[2:3], v[2:3], v[194:195] op_sel_hi:[1,0]
	v_pk_mul_f32 v[0:1], v[0:1], v[194:195] op_sel_hi:[1,0]
	s_branch .LBB0_381

.Lskipmax_A:
	v_lshl_add_u64 v[176:177], v[176:177], 0, s[56:57]
	v_lshl_add_u64 v[178:179], v[178:179], 0, s[56:57]
	v_lshl_add_u64 v[180:181], v[180:181], 0, s[56:57]
	v_lshl_add_u64 v[182:183], v[182:183], 0, s[56:57]
	v_lshl_add_u64 v[184:185], v[184:185], 0, s[58:59]
	v_lshl_add_u64 v[186:187], v[186:187], 0, s[58:59]
	v_mov_b64_e32 v[232:233], s[48:49]
	v_mov_b64_e32 v[234:235], s[50:51]
	s_branch .LBB0_381

; DI float xmax32(float x) { auto t = __builtin_amdgcn_permlane32_swap(__float_as_uint(x), __float_as_uint(x), false, false); return fmaxf(__uint_as_float(t[0]), __uint_as_float(t[1])); }
; template <int DK, int DV>
; DI void attn_map(f32x16 (&O)[DV / 32], float& lsum, const u16* qrow, const u16* K1, int ldk1, const u16* K2, int ldk2, const u16* Vt, int nkeys, char* smem) {
;     ...
;     float mx0 = fmaxf(fmaxf(s[0][0], s[0][1]), s[0][2]), mx1 = fmaxf(fmaxf(s[1][0], s[1][1]), s[1][2]);
; #pragma unroll
;     for (int i = 3; i < 15; i += 2) { mx0 = fmaxf(fmaxf(mx0, s[0][i]), s[0][i + 1]); mx1 = fmaxf(fmaxf(mx1, s[1][i]), s[1][i + 1]); }
;     float mx = fmaxf(fmaxf(mx0, mx1), fmaxf(s[0][15], s[1][15]));
;     mx = xmax32(mx);
;     const bool first = (k0 == 0);
;     if (first || __any(mx > 6.f)) {
;       float dl = first ? mx : fmaxf(mx, 0.f);
;       float alpha = __builtin_amdgcn_exp2f(-dl);
; #pragma unroll
;       for (int i = 0; i < 16; ++i) { negm[i] -= dl; lacc[i] *= alpha; }
; #pragma unroll
;       for (int dd = 0; dd < DV / 32; ++dd)
; #pragma unroll
;         for (int i = 0; i < 16; ++i) O[dd][i] *= alpha;
; #pragma unroll
;       for (int j = 0; j < 2; ++j)
; #pragma unroll
;         for (int i = 0; i < 16; ++i) s[j][i] -= dl;
;     }
.Lqk_join_B:
	s_bitcmp1_b32 s10, 6
	s_cbranch_scc1 .Lskipmax_B
	s_nop 0
	v_max3_f32 v196, v96, v97, v98
	v_lshl_add_u64 v[176:177], v[176:177], 0, s[56:57]
	v_lshl_add_u64 v[178:179], v[178:179], 0, s[56:57]
	v_lshl_add_u64 v[180:181], v[180:181], 0, s[56:57]
	v_lshl_add_u64 v[182:183], v[182:183], 0, s[56:57]
	v_lshl_add_u64 v[184:185], v[184:185], 0, s[58:59]
	v_lshl_add_u64 v[186:187], v[186:187], 0, s[58:59]
	v_mov_b64_e32 v[232:233], s[48:49]
	v_mov_b64_e32 v[234:235], s[50:51]
	s_nop 0
	v_max3_f32 v197, v112, v113, v114
	v_max3_f32 v196, v196, v99, v100
	v_max3_f32 v197, v197, v115, v116
	v_max3_f32 v196, v196, v101, v102
	v_max3_f32 v197, v197, v117, v118
	v_max3_f32 v196, v196, v103, v104
	v_max3_f32 v197, v197, v119, v120
	v_max3_f32 v196, v196, v105, v106
	v_max3_f32 v197, v197, v121, v122
	v_max3_f32 v196, v196, v107, v108
	v_max3_f32 v197, v197, v123, v124
	v_max_f32_e32 v198, v127, v127
	v_max_f32_e32 v199, v111, v111
	v_max3_f32 v196, v196, v109, v110
	v_max3_f32 v197, v197, v125, v126
	v_max_f32_e32 v198, v199, v198
	v_max3_f32 v196, v196, v197, v198
	v_cmp_lt_f32_e32 vcc, s45, v196
	s_cbranch_vccz .LBB0_403
	v_mov_b32_e32 v197, v196
	s_nop 1
	v_permlane32_swap_b32_e32 v196, v197
	v_max_f32_e32 v197, v197, v197
	v_max_f32_e32 v196, v196, v196
	v_max_f32_e32 v196, v196, v197
	v_max_f32_e32 v196, v196, v196
	v_max_f32_e32 v197, 0, v196
	v_exp_f32_e64 v196, -v197
	v_sub_f32_e32 v95, v95, v197
	v_sub_f32_e32 v94, v94, v197
	v_sub_f32_e32 v93, v93, v197
	v_pk_mul_f32 v[62:63], v[62:63], v[196:197] op_sel_hi:[1,0]
	v_pk_mul_f32 v[60:61], v[60:61], v[196:197] op_sel_hi:[1,0]
	v_pk_mul_f32 v[58:59], v[58:59], v[196:197] op_sel_hi:[1,0]
	v_pk_mul_f32 v[56:57], v[56:57], v[196:197] op_sel_hi:[1,0]
	v_pk_mul_f32 v[54:55], v[54:55], v[196:197] op_sel_hi:[1,0]
	v_pk_mul_f32 v[52:53], v[52:53], v[196:197] op_sel_hi:[1,0]
	v_pk_mul_f32 v[50:51], v[50:51], v[196:197] op_sel_hi:[1,0]
	v_pk_mul_f32 v[48:49], v[48:49], v[196:197] op_sel_hi:[1,0]
	v_pk_mul_f32 v[46:47], v[46:47], v[196:197] op_sel_hi:[1,0]
	v_pk_mul_f32 v[44:45], v[44:45], v[196:197] op_sel_hi:[1,0]
	v_pk_mul_f32 v[42:43], v[42:43], v[196:197] op_sel_hi:[1,0]
	v_pk_mul_f32 v[40:41], v[40:41], v[196:197] op_sel_hi:[1,0]
	v_pk_mul_f32 v[38:39], v[38:39], v[196:197] op_sel_hi:[1,0]
	v_pk_mul_f32 v[36:37], v[36:37], v[196:197] op_sel_hi:[1,0]
	v_pk_mul_f32 v[34:35], v[34:35], v[196:197] op_sel_hi:[1,0]
	v_pk_mul_f32 v[32:33], v[32:33], v[196:197] op_sel_hi:[1,0]
	v_pk_mul_f32 v[30:31], v[30:31], v[196:197] op_sel_hi:[1,0]
	v_pk_mul_f32 v[28:29], v[28:29], v[196:197] op_sel_hi:[1,0]
	v_pk_mul_f32 v[26:27], v[26:27], v[196:197] op_sel_hi:[1,0]
	v_pk_mul_f32 v[24:25], v[24:25], v[196:197] op_sel_hi:[1,0]
	v_pk_mul_f32 v[22:23], v[22:23], v[196:197] op_sel_hi:[1,0]
	v_pk_mul_f32 v[20:21], v[20:21], v[196:197] op_sel_hi:[1,0]
	v_pk_mul_f32 v[18:19], v[18:19], v[196:197] op_sel_hi:[1,0]
	v_pk_mul_f32 v[16:17], v[16:17], v[196:197] op_sel_hi:[1,0]
	v_pk_mul_f32 v[14:15], v[14:15], v[196:197] op_sel_hi:[1,0]
	v_pk_mul_f32 v[12:13], v[12:13], v[196:197] op_sel_hi:[1,0]
	v_pk_mul_f32 v[10:11], v[10:11], v[196:197] op_sel_hi:[1,0]
	v_pk_mul_f32 v[8:9], v[8:9], v[196:197] op_sel_hi:[1,0]
	v_pk_mul_f32 v[6:7], v[6:7], v[196:197] op_sel_hi:[1,0]
	v_pk_mul_f32 v[4:5], v[4:5], v[196:197] op_sel_hi:[1,0]
	v_pk_mul_f32 v[2:3], v[2:3], v[196:197] op_sel_hi:[1,0]
	v_pk_mul_f32 v[0:1], v[0:1], v[196:197] op_sel_hi:[1,0]
	v_sub_f32_e32 v92, v92, v197
	v_sub_f32_e32 v91, v91, v197
	v_sub_f32_e32 v90, v90, v197
	v_sub_f32_e32 v89, v89, v197
	v_sub_f32_e32 v88, v88, v197
	v_sub_f32_e32 v87, v87, v197
	v_sub_f32_e32 v86, v86, v197
	v_sub_f32_e32 v85, v85, v197
	v_sub_f32_e32 v84, v84, v197
	v_sub_f32_e32 v83, v83, v197
	v_sub_f32_e32 v82, v82, v197
	v_sub_f32_e32 v81, v81, v197
	v_sub_f32_e32 v80, v80, v197
	v_sub_f32_e32 v96, v96, v197
	v_sub_f32_e32 v97, v97, v197
	v_sub_f32_e32 v98, v98, v197
	v_sub_f32_e32 v99, v99, v197
	v_sub_f32_e32 v100, v100, v197
	v_sub_f32_e32 v101, v101, v197
	v_sub_f32_e32 v102, v102, v197
	v_sub_f32_e32 v103, v103, v197
	v_sub_f32_e32 v104, v104, v197
	v_sub_f32_e32 v105, v105, v197
	v_sub_f32_e32 v106, v106, v197
	v_sub_f32_e32 v107, v107, v197
	v_sub_f32_e32 v108, v108, v197
	v_sub_f32_e32 v109, v109, v197
	v_sub_f32_e32 v110, v110, v197
	v_sub_f32_e32 v111, v111, v197
	v_sub_f32_e32 v112, v112, v197
	v_sub_f32_e32 v113, v113, v197
	v_sub_f32_e32 v114, v114, v197
	v_sub_f32_e32 v115, v115, v197
	v_sub_f32_e32 v116, v116, v197
	v_sub_f32_e32 v117, v117, v197
	v_sub_f32_e32 v118, v118, v197
	v_sub_f32_e32 v119, v119, v197
	v_sub_f32_e32 v120, v120, v197
	v_sub_f32_e32 v121, v121, v197
	v_sub_f32_e32 v122, v122, v197
	v_sub_f32_e32 v123, v123, v197
	v_sub_f32_e32 v124, v124, v197
	v_sub_f32_e32 v125, v125, v197
	v_sub_f32_e32 v126, v126, v197
	v_sub_f32_e32 v127, v127, v197
	v_pk_mul_f32 v[78:79], v[78:79], v[196:197] op_sel_hi:[1,0]
	v_pk_mul_f32 v[76:77], v[76:77], v[196:197] op_sel_hi:[1,0]
	v_pk_mul_f32 v[74:75], v[74:75], v[196:197] op_sel_hi:[1,0]
	v_pk_mul_f32 v[72:73], v[72:73], v[196:197] op_sel_hi:[1,0]
	v_pk_mul_f32 v[70:71], v[70:71], v[196:197] op_sel_hi:[1,0]
	v_pk_mul_f32 v[68:69], v[68:69], v[196:197] op_sel_hi:[1,0]
	v_pk_mul_f32 v[66:67], v[66:67], v[196:197] op_sel_hi:[1,0]
	v_pk_mul_f32 v[64:65], v[64:65], v[196:197] op_sel_hi:[1,0]
	s_branch .LBB0_403

; DI float xmax32(float x) { auto t = __builtin_amdgcn_permlane32_swap(__float_as_uint(x), __float_as_uint(x), false, false); return fmaxf(__uint_as_float(t[0]), __uint_as_float(t[1])); }
; template <int DK, int DV>
; DI void attn_map(f32x16 (&O)[DV / 32], float& lsum, const u16* qrow, const u16* K1, int ldk1, const u16* K2, int ldk2, const u16* Vt, int nkeys, char* smem) {
;     ...
;     float mx0 = fmaxf(fmaxf(s[0][0], s[0][1]), s[0][2]), mx1 = fmaxf(fmaxf(s[1][0], s[1][1]), s[1][2]);
; #pragma unroll
;     for (int i = 3; i < 15; i += 2) { mx0 = fmaxf(fmaxf(mx0, s[0][i]), s[0][i + 1]); mx1 = fmaxf(fmaxf(mx1, s[1][i]), s[1][i + 1]); }
;     float mx = fmaxf(fmaxf(mx0, mx1), fmaxf(s[0][15], s[1][15]));
;     mx = xmax32(mx);
;     const bool first = (k0 == 0);
;     if (first || __any(mx > 6.f)) {
;       float dl = first ? mx : fmaxf(mx, 0.f);
;       float alpha = __builtin_amdgcn_exp2f(-dl);
; #pragma unroll
;       for (int i = 0; i < 16; ++i) { negm[i] -= dl; lacc[i] *= alpha; }
; #pragma unroll
;       for (int dd = 0; dd < DV / 32; ++dd)
; #pragma unroll
;         for (int i = 0; i < 16; ++i) O[dd][i] *= alpha;
; #pragma unroll
;       for (int j = 0; j < 2; ++j)
; #pragma unroll
;         for (int i = 0; i < 16; ++i) s[j][i] -= dl;
;     }
.Lqk_join_C:
	s_bitcmp1_b32 s10, 6
	s_cbranch_scc1 .Lskipmax_C
	v_max3_f32 v173, v64, v65, v66
	v_lshl_add_u64 v[154:155], v[154:155], 0, s[56:57]
	v_lshl_add_u64 v[156:157], v[156:157], 0, s[56:57]
	v_mov_b64_e32 v[184:185], s[48:49]
	v_mov_b64_e32 v[186:187], s[50:51]
	s_nop 5
	v_max3_f32 v174, v80, v81, v82
	v_max3_f32 v173, v173, v67, v68
	v_max3_f32 v174, v174, v83, v84
	v_max3_f32 v173, v173, v69, v70
	v_max3_f32 v174, v174, v85, v86
	v_max3_f32 v173, v173, v71, v72
	v_max3_f32 v174, v174, v87, v88
	v_max3_f32 v173, v173, v73, v74
	v_max3_f32 v174, v174, v89, v90
	v_max3_f32 v173, v173, v75, v76
	v_max3_f32 v174, v174, v91, v92
	v_max_f32_e32 v175, v95, v95
	v_max_f32_e32 v176, v79, v79
	v_max3_f32 v173, v173, v77, v78
	v_max3_f32 v174, v174, v93, v94
	v_max_f32_e32 v175, v176, v175
	v_max3_f32 v173, v173, v174, v175
	v_cmp_lt_f32_e32 vcc, s45, v173
	s_cbranch_vccz .LBB0_440
	v_mov_b32_e32 v174, v173
	s_nop 1
	v_permlane32_swap_b32_e32 v173, v174
	v_max_f32_e32 v174, v174, v174
	v_max_f32_e32 v173, v173, v173
	v_max_f32_e32 v173, v173, v174
	v_max_f32_e32 v173, v173, v173
	v_max_f32_e32 v173, 0, v173
	v_exp_f32_e64 v174, -v173
	v_sub_f32_e32 v31, v31, v173
	v_sub_f32_e32 v30, v30, v173
	v_sub_f32_e32 v29, v29, v173
	v_pk_mul_f32 v[62:63], v[62:63], v[174:175] op_sel_hi:[1,0]
	v_pk_mul_f32 v[60:61], v[60:61], v[174:175] op_sel_hi:[1,0]
	v_pk_mul_f32 v[58:59], v[58:59], v[174:175] op_sel_hi:[1,0]
	v_pk_mul_f32 v[56:57], v[56:57], v[174:175] op_sel_hi:[1,0]
	v_pk_mul_f32 v[54:55], v[54:55], v[174:175] op_sel_hi:[1,0]
	v_pk_mul_f32 v[52:53], v[52:53], v[174:175] op_sel_hi:[1,0]
	v_pk_mul_f32 v[50:51], v[50:51], v[174:175] op_sel_hi:[1,0]
	v_pk_mul_f32 v[48:49], v[48:49], v[174:175] op_sel_hi:[1,0]
	v_pk_mul_f32 v[46:47], v[46:47], v[174:175] op_sel_hi:[1,0]
	v_pk_mul_f32 v[44:45], v[44:45], v[174:175] op_sel_hi:[1,0]
	v_pk_mul_f32 v[42:43], v[42:43], v[174:175] op_sel_hi:[1,0]
	v_pk_mul_f32 v[40:41], v[40:41], v[174:175] op_sel_hi:[1,0]
	v_pk_mul_f32 v[38:39], v[38:39], v[174:175] op_sel_hi:[1,0]
	v_pk_mul_f32 v[36:37], v[36:37], v[174:175] op_sel_hi:[1,0]
	v_pk_mul_f32 v[34:35], v[34:35], v[174:175] op_sel_hi:[1,0]
	v_pk_mul_f32 v[32:33], v[32:33], v[174:175] op_sel_hi:[1,0]
	v_sub_f32_e32 v28, v28, v173
	v_sub_f32_e32 v27, v27, v173
	v_sub_f32_e32 v26, v26, v173
	v_sub_f32_e32 v25, v25, v173
	v_sub_f32_e32 v24, v24, v173
	v_sub_f32_e32 v23, v23, v173
	v_sub_f32_e32 v22, v22, v173
	v_sub_f32_e32 v21, v21, v173
	v_sub_f32_e32 v20, v20, v173
	v_sub_f32_e32 v19, v19, v173
	v_sub_f32_e32 v18, v18, v173
	v_sub_f32_e32 v17, v17, v173
	v_sub_f32_e32 v16, v16, v173
	v_sub_f32_e32 v64, v64, v173
	v_sub_f32_e32 v65, v65, v173
	v_sub_f32_e32 v66, v66, v173
	v_sub_f32_e32 v67, v67, v173
	v_sub_f32_e32 v68, v68, v173
	v_sub_f32_e32 v69, v69, v173
	v_sub_f32_e32 v70, v70, v173
	v_sub_f32_e32 v71, v71, v173
	v_sub_f32_e32 v72, v72, v173
	v_sub_f32_e32 v73, v73, v173
	v_sub_f32_e32 v74, v74, v173
	v_sub_f32_e32 v75, v75, v173
	v_sub_f32_e32 v76, v76, v173
	v_sub_f32_e32 v77, v77, v173
	v_sub_f32_e32 v78, v78, v173
	v_sub_f32_e32 v79, v79, v173
	v_sub_f32_e32 v80, v80, v173
	v_sub_f32_e32 v81, v81, v173
	v_sub_f32_e32 v82, v82, v173
	v_sub_f32_e32 v83, v83, v173
	v_sub_f32_e32 v84, v84, v173
	v_sub_f32_e32 v85, v85, v173
	v_sub_f32_e32 v86, v86, v173
	v_sub_f32_e32 v87, v87, v173
	v_sub_f32_e32 v88, v88, v173
	v_sub_f32_e32 v89, v89, v173
	v_sub_f32_e32 v90, v90, v173
	v_sub_f32_e32 v91, v91, v173
	v_sub_f32_e32 v92, v92, v173
	v_sub_f32_e32 v93, v93, v173
	v_sub_f32_e32 v94, v94, v173
	v_sub_f32_e32 v95, v95, v173
	v_pk_mul_f32 v[14:15], v[14:15], v[174:175] op_sel_hi:[1,0]
	v_pk_mul_f32 v[12:13], v[12:13], v[174:175] op_sel_hi:[1,0]
	v_pk_mul_f32 v[10:11], v[10:11], v[174:175] op_sel_hi:[1,0]
	v_pk_mul_f32 v[8:9], v[8:9], v[174:175] op_sel_hi:[1,0]
	v_pk_mul_f32 v[6:7], v[6:7], v[174:175] op_sel_hi:[1,0]
	v_pk_mul_f32 v[4:5], v[4:5], v[174:175] op_sel_hi:[1,0]
	v_pk_mul_f32 v[2:3], v[2:3], v[174:175] op_sel_hi:[1,0]
	v_pk_mul_f32 v[0:1], v[0:1], v[174:175] op_sel_hi:[1,0]

.Lskipmax_C:
	v_lshl_add_u64 v[154:155], v[154:155], 0, s[56:57]
	v_lshl_add_u64 v[156:157], v[156:157], 0, s[56:57]
	v_mov_b64_e32 v[184:185], s[48:49]
	v_mov_b64_e32 v[186:187], s[50:51]
	s_branch .LBB0_440

; DI float xmax32(float x) { auto t = __builtin_amdgcn_permlane32_swap(__float_as_uint(x), __float_as_uint(x), false, false); return fmaxf(__uint_as_float(t[0]), __uint_as_float(t[1])); }
; template <int DK, int DV>
; DI void attn_map(f32x16 (&O)[DV / 32], float& lsum, const u16* qrow, const u16* K1, int ldk1, const u16* K2, int ldk2, const u16* Vt, int nkeys, char* smem) {
;     ...
;     float mx0 = fmaxf(fmaxf(s[0][0], s[0][1]), s[0][2]), mx1 = fmaxf(fmaxf(s[1][0], s[1][1]), s[1][2]);
; #pragma unroll
;     for (int i = 3; i < 15; i += 2) { mx0 = fmaxf(fmaxf(mx0, s[0][i]), s[0][i + 1]); mx1 = fmaxf(fmaxf(mx1, s[1][i]), s[1][i + 1]); }
;     float mx = fmaxf(fmaxf(mx0, mx1), fmaxf(s[0][15], s[1][15]));
;     mx = xmax32(mx);
;     const bool first = (k0 == 0);
;     if (first || __any(mx > 6.f)) {
;       float dl = first ? mx : fmaxf(mx, 0.f);
;       float alpha = __builtin_amdgcn_exp2f(-dl);
; #pragma unroll
;       for (int i = 0; i < 16; ++i) { negm[i] -= dl; lacc[i] *= alpha; }
; #pragma unroll
;       for (int dd = 0; dd < DV / 32; ++dd)
; #pragma unroll
;         for (int i = 0; i < 16; ++i) O[dd][i] *= alpha;
; #pragma unroll
;       for (int j = 0; j < 2; ++j)
; #pragma unroll
;         for (int i = 0; i < 16; ++i) s[j][i] -= dl;
;     }
.Lqk_join_D:
	s_bitcmp1_b32 s12, 6
	s_cbranch_scc1 .Lskipmax_D
	s_nop 0
	v_max3_f32 v144, v64, v65, v66
	s_mov_b64 s[10:11], 0x4000
	v_lshl_add_u64 v[130:131], v[130:131], 0, s[56:57]
	v_lshl_add_u64 v[132:133], v[132:133], 0, s[56:57]
	v_lshl_add_u64 v[134:135], v[134:135], 0, s[10:11]
	v_lshl_add_u64 v[136:137], v[136:137], 0, s[10:11]
	v_mov_b64_e32 v[232:233], s[48:49]
	v_mov_b64_e32 v[234:235], s[50:51]
	s_nop 1
	v_max3_f32 v145, v80, v81, v82
	v_max3_f32 v144, v144, v67, v68
	v_max3_f32 v145, v145, v83, v84
	v_max3_f32 v144, v144, v69, v70
	v_max3_f32 v145, v145, v85, v86
	v_max3_f32 v144, v144, v71, v72
	v_max3_f32 v145, v145, v87, v88
	v_max3_f32 v144, v144, v73, v74
	v_max3_f32 v145, v145, v89, v90
	v_max3_f32 v144, v144, v75, v76
	v_max3_f32 v145, v145, v91, v92
	v_max_f32_e32 v146, v95, v95
	v_max_f32_e32 v147, v79, v79
	v_max3_f32 v144, v144, v77, v78
	v_max3_f32 v145, v145, v93, v94
	v_max_f32_e32 v146, v147, v146
	v_max3_f32 v144, v144, v145, v146
	v_cmp_lt_f32_e32 vcc, s45, v144
	s_cbranch_vccz .LBB0_446
	v_mov_b32_e32 v145, v144
	s_nop 1
	v_permlane32_swap_b32_e32 v144, v145
	v_max_f32_e32 v145, v145, v145
	v_max_f32_e32 v144, v144, v144
	v_max_f32_e32 v144, v144, v145
	v_max_f32_e32 v144, v144, v144
	v_max_f32_e32 v145, 0, v144
	v_exp_f32_e64 v144, -v145
	v_sub_f32_e32 v31, v31, v145
	v_sub_f32_e32 v30, v30, v145
	v_sub_f32_e32 v29, v29, v145
	v_pk_mul_f32 v[62:63], v[62:63], v[144:145] op_sel_hi:[1,0]
	v_pk_mul_f32 v[60:61], v[60:61], v[144:145] op_sel_hi:[1,0]
	v_pk_mul_f32 v[58:59], v[58:59], v[144:145] op_sel_hi:[1,0]
	v_pk_mul_f32 v[56:57], v[56:57], v[144:145] op_sel_hi:[1,0]
	v_pk_mul_f32 v[54:55], v[54:55], v[144:145] op_sel_hi:[1,0]
	v_pk_mul_f32 v[52:53], v[52:53], v[144:145] op_sel_hi:[1,0]
	v_pk_mul_f32 v[50:51], v[50:51], v[144:145] op_sel_hi:[1,0]
	v_pk_mul_f32 v[48:49], v[48:49], v[144:145] op_sel_hi:[1,0]
	v_pk_mul_f32 v[46:47], v[46:47], v[144:145] op_sel_hi:[1,0]
	v_pk_mul_f32 v[44:45], v[44:45], v[144:145] op_sel_hi:[1,0]
	v_pk_mul_f32 v[42:43], v[42:43], v[144:145] op_sel_hi:[1,0]
	v_pk_mul_f32 v[40:41], v[40:41], v[144:145] op_sel_hi:[1,0]
	v_pk_mul_f32 v[38:39], v[38:39], v[144:145] op_sel_hi:[1,0]
	v_pk_mul_f32 v[36:37], v[36:37], v[144:145] op_sel_hi:[1,0]
	v_pk_mul_f32 v[34:35], v[34:35], v[144:145] op_sel_hi:[1,0]
	v_pk_mul_f32 v[32:33], v[32:33], v[144:145] op_sel_hi:[1,0]
	v_sub_f32_e32 v28, v28, v145
	v_sub_f32_e32 v27, v27, v145
	v_sub_f32_e32 v26, v26, v145
	v_sub_f32_e32 v25, v25, v145
	v_sub_f32_e32 v24, v24, v145
	v_sub_f32_e32 v23, v23, v145
	v_sub_f32_e32 v22, v22, v145
	v_sub_f32_e32 v21, v21, v145
	v_sub_f32_e32 v20, v20, v145
	v_sub_f32_e32 v19, v19, v145
	v_sub_f32_e32 v18, v18, v145
	v_sub_f32_e32 v17, v17, v145
	v_sub_f32_e32 v16, v16, v145
	v_sub_f32_e32 v64, v64, v145
	v_sub_f32_e32 v65, v65, v145
	v_sub_f32_e32 v66, v66, v145
	v_sub_f32_e32 v67, v67, v145
	v_sub_f32_e32 v68, v68, v145
	v_sub_f32_e32 v69, v69, v145
	v_sub_f32_e32 v70, v70, v145
	v_sub_f32_e32 v71, v71, v145
	v_sub_f32_e32 v72, v72, v145
	v_sub_f32_e32 v73, v73, v145
	v_sub_f32_e32 v74, v74, v145
	v_sub_f32_e32 v75, v75, v145
	v_sub_f32_e32 v76, v76, v145
	v_sub_f32_e32 v77, v77, v145
	v_sub_f32_e32 v78, v78, v145
	v_sub_f32_e32 v79, v79, v145
	v_sub_f32_e32 v80, v80, v145
	v_sub_f32_e32 v81, v81, v145
	v_sub_f32_e32 v82, v82, v145
	v_sub_f32_e32 v83, v83, v145
	v_sub_f32_e32 v84, v84, v145
	v_sub_f32_e32 v85, v85, v145
	v_sub_f32_e32 v86, v86, v145
	v_sub_f32_e32 v87, v87, v145
	v_sub_f32_e32 v88, v88, v145
	v_sub_f32_e32 v89, v89, v145
	v_sub_f32_e32 v90, v90, v145
	v_sub_f32_e32 v91, v91, v145
	v_sub_f32_e32 v92, v92, v145
	v_sub_f32_e32 v93, v93, v145
	v_sub_f32_e32 v94, v94, v145
	v_sub_f32_e32 v95, v95, v145
	v_pk_mul_f32 v[14:15], v[14:15], v[144:145] op_sel_hi:[1,0]
	v_pk_mul_f32 v[12:13], v[12:13], v[144:145] op_sel_hi:[1,0]
	v_pk_mul_f32 v[10:11], v[10:11], v[144:145] op_sel_hi:[1,0]
	v_pk_mul_f32 v[8:9], v[8:9], v[144:145] op_sel_hi:[1,0]
	v_pk_mul_f32 v[6:7], v[6:7], v[144:145] op_sel_hi:[1,0]
	v_pk_mul_f32 v[4:5], v[4:5], v[144:145] op_sel_hi:[1,0]
	v_pk_mul_f32 v[2:3], v[2:3], v[144:145] op_sel_hi:[1,0]
	v_pk_mul_f32 v[0:1], v[0:1], v[144:145] op_sel_hi:[1,0]
	s_branch .LBB0_446

.Lskipmax_D:
	s_mov_b64 s[10:11], 0x4000
	v_lshl_add_u64 v[130:131], v[130:131], 0, s[56:57]
	v_lshl_add_u64 v[132:133], v[132:133], 0, s[56:57]
	v_lshl_add_u64 v[134:135], v[134:135], 0, s[10:11]
	v_lshl_add_u64 v[136:137], v[136:137], 0, s[10:11]
	v_mov_b64_e32 v[232:233], s[48:49]
	v_mov_b64_e32 v[234:235], s[50:51]
	s_branch .LBB0_446
